# grid barrier spin loops: s_sleep 1 back-off between polls so waiting workgroups stop hammering the generation words while others still compute
# baseline (speedup 1.0000x reference)
.LBB0_563:
	v_readlane_b32 s8, v253, 6
	v_readlane_b32 s9, v253, 7
	s_add_i32 s1, s1, 1
	s_sleep 1
	s_mov_b64 s[40:41], -1
	s_nop 2
	global_load_dword v0, v51, s[8:9] sc1
	s_waitcnt vmcnt(0)
	v_cmp_ne_u32_e32 vcc, v0, v1
	s_orn2_b64 s[38:39], vcc, exec
	s_branch .LBB0_560

.LBB0_580:
	v_readlane_b32 s8, v253, 10
	v_readlane_b32 s9, v253, 11
	s_add_i32 s1, s1, 1
	s_sleep 1
	s_mov_b64 s[40:41], -1
	s_nop 2
	global_load_dword v0, v51, s[8:9] sc1
	s_waitcnt vmcnt(0)
	v_cmp_ne_u32_e32 vcc, v0, v2
	s_orn2_b64 s[38:39], vcc, exec
	s_branch .LBB0_577
